# speedup vs baseline: 1.0134x; 1.0070x over previous
; __global__ void __launch_bounds__(NTHR, 2) hymba_fwd(Args args) {
;     ...
;     if (args.ph_hi - args.ph_lo > 1) grid.sync();
.LBB0_5:
	s_or_b64 exec, exec, s[2:3]
.LBB0_17:
	s_cmp_le_i32 s55, s54
	s_cbranch_scc0 .LBB0_18
	s_getpc_b64 s[98:99]

; __device__ __forceinline__ unsigned cvt_pk_bf16(float lo, float hi) { unsigned r; asm volatile("v_cvt_pk_bf16_f32 %0, %1, %2" : "=v"(r) : "v"(lo), "v"(hi)); return r; }
; __device__ __forceinline__ float dot4(f32x4 a, f32x4 b) { return (a.x * b.x + a.y * b.y) + (a.z * b.z + a.w * b.w); }
; __device__ __forceinline__ void group_norm_rows(const float* Y, const float* RW, const LayerP& L, bf16* dst, int gw, int NGW, int lane) {
;     for (int m = gw; m < T; m += NGW) {
; #pragma unroll
;         for (int gi = 0; gi < 4; ++gi) {
;             const float* yr = Y + (size_t)m * D + gi * GW;
;             f32x4 a = ((const f32x4*)yr)[lane], b = ((const f32x4*)yr)[64 + lane];
;             if (gi == 2) {
;                 const int ca = 4 * lane, cb = 256 + 4 * lane;
;                 const float ma = row16_sum((a.x + a.y) + (a.z + a.w)) * (1.f / 64.f), mb = row16_sum((b.x + b.y) + (b.z + b.w)) * (1.f / 64.f);
;                 const f32x4 da = a - ma, db = b - mb;
;                 const float ra = rsqrtf(row16_sum(dot4(da, da)) * (1.f / 64.f) + 64e-5f), rb = rsqrtf(row16_sum(dot4(db, db)) * (1.f / 64.f) + 64e-5f);
;                 const f32x4 ga = *(const f32x4*)(L.rw_lng + ca), gb = *(const f32x4*)(L.rw_lng + cb), ba = *(const f32x4*)(L.rw_lnb + ca), bb = *(const f32x4*)(L.rw_lnb + cb);
;                 const f32x4 bna = *(const f32x4*)(RW + 7 * RWSZ + (size_t)m * GW + ca), bnb = *(const f32x4*)(RW + 7 * RWSZ + (size_t)m * GW + cb);
;                 const f32x4 gga = *(const f32x4*)(RW + 6 * RWSZ + (size_t)m * GW + ca), ggb = *(const f32x4*)(RW + 6 * RWSZ + (size_t)m * GW + cb);
;                 a = (da * ra * ga + ba + bna) * gga; b = (db * rb * gb + bb + bnb) * ggb;
;             }
;             const float ss = wave_sum(dot4(a, a) + dot4(b, b));
;             const float rstd = rsqrtf(ss * (1.f / GW) + 1e-6f);
;             const f32x4 na = ((const f32x4*)(L.out_norm + gi * GW))[lane], nb = ((const f32x4*)(L.out_norm + gi * GW))[64 + lane];
;             const f32x4 oa = a * rstd * na, ob = b * rstd * nb;
;             u32x2 w; w.x = pg8::cvt_pk_bf16(oa.x, oa.y); w.y = pg8::cvt_pk_bf16(oa.z, oa.w); ((u32x2*)(dst + (size_t)m * D + gi * GW))[lane] = w;
;             w.x = pg8::cvt_pk_bf16(ob.x, ob.y); w.y = pg8::cvt_pk_bf16(ob.z, ob.w); ((u32x2*)(dst + (size_t)m * D + gi * GW))[64 + lane] = w;
.LBB0_61:
	s_and_b64 vcc, exec, s[0:1]
	v_readlane_b32 s14, v254, 42
	v_readlane_b32 s15, v254, 43
	s_cbranch_vccz .LBB0_65
	v_readlane_b32 s0, v254, 40
	s_cmpk_gt_i32 s0, 0x1fff
	v_readlane_b32 s1, v254, 41
	s_cbranch_scc1 .LBB0_65
	s_mov_b32 s30, s0
	s_waitcnt vmcnt(0) lgkmcnt(0)
	v_readlane_b32 s8, v254, 32
	v_readlane_b32 s9, v254, 33
	v_readlane_b32 s10, v254, 30
	s_nop 0
	s_load_dwordx2 s[4:5], s[8:9], 0x140
	s_load_dwordx4 s[20:23], s[8:9], 0xf8
	s_ashr_i32 s11, s10, 31
	v_lshlrev_b32_e32 v0, 4, v188
	v_add_u32_e32 v1, 0x1000, v0
	v_lshlrev_b32_e32 v2, 3, v188
	s_lshl_b64 s[0:1], s[10:11], 13
	s_lshl_b64 s[6:7], s[10:11], 11
	s_waitcnt lgkmcnt(0)
	s_add_u32 s4, s4, s0
	s_addc_u32 s5, s5, s1
	s_add_u32 s20, s20, s6
	s_addc_u32 s21, s21, s7
	s_add_u32 s22, s22, s6
	s_addc_u32 s23, s23, s7
	global_load_dwordx4 v[80:83], v0, s[4:5] offset:0
	global_load_dwordx4 v[84:87], v0, s[4:5] offset:1024
	global_load_dwordx4 v[88:91], v0, s[4:5] offset:2048
	global_load_dwordx4 v[92:95], v0, s[4:5] offset:3072
	global_load_dwordx4 v[96:99], v1, s[4:5] offset:0
	global_load_dwordx4 v[100:103], v1, s[4:5] offset:1024
	global_load_dwordx4 v[104:107], v1, s[4:5] offset:2048
	global_load_dwordx4 v[108:111], v1, s[4:5] offset:3072
	global_load_dwordx4 v[112:115], v0, s[20:21]
	global_load_dwordx4 v[116:119], v0, s[20:21] offset:1024
	global_load_dwordx4 v[120:123], v0, s[22:23]
	global_load_dwordx4 v[124:127], v0, s[22:23] offset:1024
	v_readlane_b32 s0, v254, 38
	s_cmp_eq_u32 s0, 0x100
	s_cbranch_scc1 .Lgn2_row
.Lgn_row:
	s_lshl_b32 s0, s30, 13
	s_add_u32 s20, s18, s0
	s_addc_u32 s21, s19, 0
	s_add_u32 s20, s20, 0x1e200000
	s_addc_u32 s21, s21, 0
	s_lshl_b32 s0, s30, 11
	s_add_u32 s22, s18, s0
	s_addc_u32 s23, s19, 0
	s_add_u32 s24, s22, 0x1d200000
	s_addc_u32 s25, s23, 0
	s_add_u32 s22, s22, 0x1c200000
	s_addc_u32 s23, s23, 0
	s_lshl_b32 s0, s30, 12
	s_add_u32 s26, s18, s0
	s_addc_u32 s27, s19, 0
	s_add_u32 s26, s26, 0x22200000
	s_addc_u32 s27, s27, 0
	global_load_dwordx4 v[16:19], v0, s[20:21]
	global_load_dwordx4 v[20:23], v0, s[20:21] offset:1024
	global_load_dwordx4 v[24:27], v0, s[20:21] offset:2048
	global_load_dwordx4 v[28:31], v0, s[20:21] offset:3072
	global_load_dwordx4 v[40:43], v1, s[20:21] offset:2048
	global_load_dwordx4 v[44:47], v1, s[20:21] offset:3072
	global_load_dwordx4 v[32:35], v1, s[20:21]
	global_load_dwordx4 v[36:39], v1, s[20:21] offset:1024
	global_load_dwordx4 v[48:51], v0, s[24:25]
	global_load_dwordx4 v[52:55], v0, s[24:25] offset:1024
	global_load_dwordx4 v[56:59], v0, s[22:23]
	global_load_dwordx4 v[60:63], v0, s[22:23] offset:1024
	s_waitcnt vmcnt(10)
	v_mul_f32_e32 v3, v16, v16
	v_fmac_f32_e32 v3, v17, v17
	v_mul_f32_e32 v4, v18, v18
	v_fmac_f32_e32 v4, v19, v19
	v_add_f32_e32 v3, v3, v4
	v_mul_f32_e32 v5, v20, v20
	v_fmac_f32_e32 v5, v21, v21
	v_mul_f32_e32 v6, v22, v22
	v_fmac_f32_e32 v6, v23, v23
	v_add_f32_e32 v5, v5, v6
	v_add_f32_e32 v3, v3, v5
	s_nop 1
	v_add_f32_dpp v3, v3, v3 quad_perm:[1,0,3,2] row_mask:0xf bank_mask:0xf bound_ctrl:1
	s_nop 1
	v_add_f32_dpp v3, v3, v3 quad_perm:[2,3,0,1] row_mask:0xf bank_mask:0xf bound_ctrl:1
	s_nop 1
	v_add_f32_dpp v3, v3, v3 row_half_mirror row_mask:0xf bank_mask:0xf bound_ctrl:1
	s_nop 1
	v_add_f32_dpp v3, v3, v3 row_mirror row_mask:0xf bank_mask:0xf bound_ctrl:1
	s_nop 1
	v_readlane_b32 s0, v3, 0
	v_readlane_b32 s1, v3, 16
	v_readlane_b32 s8, v3, 32
	v_readlane_b32 s9, v3, 48
	s_nop 1
	v_mov_b32_e32 v4, s0
	v_add_f32_e32 v4, s1, v4
	v_add_f32_e32 v4, s8, v4
	v_add_f32_e32 v4, s9, v4
	v_mov_b32_e32 v5, 0x3b000000
	v_fma_f32 v4, v4, v5, v173
	v_rsq_f32_e32 v4, v4
	s_nop 0
	v_mul_f32_e32 v8, v16, v4
	v_mul_f32_e32 v8, v8, v80
	v_mul_f32_e32 v9, v17, v4
	v_mul_f32_e32 v9, v9, v81
	v_mul_f32_e32 v10, v18, v4
	v_mul_f32_e32 v10, v10, v82
	v_mul_f32_e32 v11, v19, v4
	v_mul_f32_e32 v11, v11, v83
	v_cvt_pk_bf16_f32 v12, v8, v9
	v_cvt_pk_bf16_f32 v13, v10, v11
	global_store_dwordx2 v2, v[12:13], s[26:27] offset:0
	v_mul_f32_e32 v8, v20, v4
	v_mul_f32_e32 v8, v8, v84
	v_mul_f32_e32 v9, v21, v4
	v_mul_f32_e32 v9, v9, v85
	v_mul_f32_e32 v10, v22, v4
	v_mul_f32_e32 v10, v10, v86
	v_mul_f32_e32 v11, v23, v4
	v_mul_f32_e32 v11, v11, v87
	v_cvt_pk_bf16_f32 v12, v8, v9
	v_cvt_pk_bf16_f32 v13, v10, v11
	global_store_dwordx2 v2, v[12:13], s[26:27] offset:512
	s_waitcnt vmcnt(10)
	v_mul_f32_e32 v3, v24, v24
	v_fmac_f32_e32 v3, v25, v25
	v_mul_f32_e32 v4, v26, v26
	v_fmac_f32_e32 v4, v27, v27
	v_add_f32_e32 v3, v3, v4
	v_mul_f32_e32 v5, v28, v28
	v_fmac_f32_e32 v5, v29, v29
	v_mul_f32_e32 v6, v30, v30
	v_fmac_f32_e32 v6, v31, v31
	v_add_f32_e32 v5, v5, v6
	v_add_f32_e32 v3, v3, v5
	s_nop 1
	v_add_f32_dpp v3, v3, v3 quad_perm:[1,0,3,2] row_mask:0xf bank_mask:0xf bound_ctrl:1
	s_nop 1
	v_add_f32_dpp v3, v3, v3 quad_perm:[2,3,0,1] row_mask:0xf bank_mask:0xf bound_ctrl:1
	s_nop 1
	v_add_f32_dpp v3, v3, v3 row_half_mirror row_mask:0xf bank_mask:0xf bound_ctrl:1
	s_nop 1
	v_add_f32_dpp v3, v3, v3 row_mirror row_mask:0xf bank_mask:0xf bound_ctrl:1
	s_nop 1
	v_readlane_b32 s0, v3, 0
	v_readlane_b32 s1, v3, 16
	v_readlane_b32 s8, v3, 32
	v_readlane_b32 s9, v3, 48
	s_nop 1
	v_mov_b32_e32 v4, s0
	v_add_f32_e32 v4, s1, v4
	v_add_f32_e32 v4, s8, v4
	v_add_f32_e32 v4, s9, v4
	v_mov_b32_e32 v5, 0x3b000000
	v_fma_f32 v4, v4, v5, v173
	v_rsq_f32_e32 v4, v4
	s_nop 0
	v_mul_f32_e32 v8, v24, v4
	v_mul_f32_e32 v8, v8, v88
	v_mul_f32_e32 v9, v25, v4
	v_mul_f32_e32 v9, v9, v89
	v_mul_f32_e32 v10, v26, v4
	v_mul_f32_e32 v10, v10, v90
	v_mul_f32_e32 v11, v27, v4
	v_mul_f32_e32 v11, v11, v91
	v_cvt_pk_bf16_f32 v12, v8, v9
	v_cvt_pk_bf16_f32 v13, v10, v11
	global_store_dwordx2 v2, v[12:13], s[26:27] offset:1024
	v_mul_f32_e32 v8, v28, v4
	v_mul_f32_e32 v8, v8, v92
	v_mul_f32_e32 v9, v29, v4
	v_mul_f32_e32 v9, v9, v93
	v_mul_f32_e32 v10, v30, v4
	v_mul_f32_e32 v10, v10, v94
	v_mul_f32_e32 v11, v31, v4
	v_mul_f32_e32 v11, v11, v95
	v_cvt_pk_bf16_f32 v12, v8, v9
	v_cvt_pk_bf16_f32 v13, v10, v11
	global_store_dwordx2 v2, v[12:13], s[26:27] offset:1536
	s_waitcnt vmcnt(10)
; __device__ __forceinline__ unsigned cvt_pk_bf16(float lo, float hi) { unsigned r; asm volatile("v_cvt_pk_bf16_f32 %0, %1, %2" : "=v"(r) : "v"(lo), "v"(hi)); return r; }
; __device__ __forceinline__ float dot4(f32x4 a, f32x4 b) { return (a.x * b.x + a.y * b.y) + (a.z * b.z + a.w * b.w); }
; __device__ __forceinline__ void group_norm_rows(const float* Y, const float* RW, const LayerP& L, bf16* dst, int gw, int NGW, int lane) {
;     ...
;             if (gi == 2) {
;                 const int ca = 4 * lane, cb = 256 + 4 * lane;
;                 const float ma = row16_sum((a.x + a.y) + (a.z + a.w)) * (1.f / 64.f), mb = row16_sum((b.x + b.y) + (b.z + b.w)) * (1.f / 64.f);
;                 const f32x4 da = a - ma, db = b - mb;
;                 const float ra = rsqrtf(row16_sum(dot4(da, da)) * (1.f / 64.f) + 64e-5f), rb = rsqrtf(row16_sum(dot4(db, db)) * (1.f / 64.f) + 64e-5f);
;                 const f32x4 ga = *(const f32x4*)(L.rw_lng + ca), gb = *(const f32x4*)(L.rw_lng + cb), ba = *(const f32x4*)(L.rw_lnb + ca), bb = *(const f32x4*)(L.rw_lnb + cb);
;                 const f32x4 bna = *(const f32x4*)(RW + 7 * RWSZ + (size_t)m * GW + ca), bnb = *(const f32x4*)(RW + 7 * RWSZ + (size_t)m * GW + cb);
;                 const f32x4 gga = *(const f32x4*)(RW + 6 * RWSZ + (size_t)m * GW + ca), ggb = *(const f32x4*)(RW + 6 * RWSZ + (size_t)m * GW + cb);
;                 a = (da * ra * ga + ba + bna) * gga; b = (db * rb * gb + bb + bnb) * ggb;
;             }
;             const float ss = wave_sum(dot4(a, a) + dot4(b, b));
;             const float rstd = rsqrtf(ss * (1.f / GW) + 1e-6f);
;             const f32x4 na = ((const f32x4*)(L.out_norm + gi * GW))[lane], nb = ((const f32x4*)(L.out_norm + gi * GW))[64 + lane];
;             const f32x4 oa = a * rstd * na, ob = b * rstd * nb;
;             u32x2 w; w.x = pg8::cvt_pk_bf16(oa.x, oa.y); w.y = pg8::cvt_pk_bf16(oa.z, oa.w); ((u32x2*)(dst + (size_t)m * D + gi * GW))[lane] = w;
;             w.x = pg8::cvt_pk_bf16(ob.x, ob.y); w.y = pg8::cvt_pk_bf16(ob.z, ob.w); ((u32x2*)(dst + (size_t)m * D + gi * GW))[64 + lane] = w;
;         }
;     }
	v_mul_f32_e32 v3, v40, v40
	v_fmac_f32_e32 v3, v41, v41
	v_mul_f32_e32 v4, v42, v42
	v_fmac_f32_e32 v4, v43, v43
	v_add_f32_e32 v3, v3, v4
	v_mul_f32_e32 v5, v44, v44
	v_fmac_f32_e32 v5, v45, v45
	v_mul_f32_e32 v6, v46, v46
	v_fmac_f32_e32 v6, v47, v47
	v_add_f32_e32 v5, v5, v6
	v_add_f32_e32 v3, v3, v5
	s_nop 1
	v_add_f32_dpp v3, v3, v3 quad_perm:[1,0,3,2] row_mask:0xf bank_mask:0xf bound_ctrl:1
	s_nop 1
	v_add_f32_dpp v3, v3, v3 quad_perm:[2,3,0,1] row_mask:0xf bank_mask:0xf bound_ctrl:1
	s_nop 1
	v_add_f32_dpp v3, v3, v3 row_half_mirror row_mask:0xf bank_mask:0xf bound_ctrl:1
	s_nop 1
	v_add_f32_dpp v3, v3, v3 row_mirror row_mask:0xf bank_mask:0xf bound_ctrl:1
	s_nop 1
	v_readlane_b32 s0, v3, 0
	v_readlane_b32 s1, v3, 16
	v_readlane_b32 s8, v3, 32
	v_readlane_b32 s9, v3, 48
	s_nop 1
	v_mov_b32_e32 v4, s0
	v_add_f32_e32 v4, s1, v4
	v_add_f32_e32 v4, s8, v4
	v_add_f32_e32 v4, s9, v4
	v_mov_b32_e32 v5, 0x3b000000
	v_fma_f32 v4, v4, v5, v173
	v_rsq_f32_e32 v4, v4
	s_nop 0
	v_mul_f32_e32 v8, v40, v4
	v_mul_f32_e32 v8, v8, v104
	v_mul_f32_e32 v9, v41, v4
	v_mul_f32_e32 v9, v9, v105
	v_mul_f32_e32 v10, v42, v4
	v_mul_f32_e32 v10, v10, v106
	v_mul_f32_e32 v11, v43, v4
	v_mul_f32_e32 v11, v11, v107
	v_cvt_pk_bf16_f32 v12, v8, v9
	v_cvt_pk_bf16_f32 v13, v10, v11
	global_store_dwordx2 v2, v[12:13], s[26:27] offset:3072
	v_mul_f32_e32 v8, v44, v4
	v_mul_f32_e32 v8, v8, v108
	v_mul_f32_e32 v9, v45, v4
	v_mul_f32_e32 v9, v9, v109
	v_mul_f32_e32 v10, v46, v4
	v_mul_f32_e32 v10, v10, v110
	v_mul_f32_e32 v11, v47, v4
	v_mul_f32_e32 v11, v11, v111
	v_cvt_pk_bf16_f32 v12, v8, v9
	v_cvt_pk_bf16_f32 v13, v10, v11
	global_store_dwordx2 v2, v[12:13], s[26:27] offset:3584
	s_waitcnt vmcnt(6)
	v_add_f32_e32 v64, v32, v33
	v_add_f32_e32 v3, v34, v35
	v_add_f32_e32 v64, v64, v3
	v_add_f32_e32 v65, v36, v37
	v_add_f32_e32 v3, v38, v39
	v_add_f32_e32 v65, v65, v3
	s_nop 1
	v_add_f32_dpp v64, v64, v64 quad_perm:[1,0,3,2] row_mask:0xf bank_mask:0xf bound_ctrl:1
	v_add_f32_dpp v65, v65, v65 quad_perm:[1,0,3,2] row_mask:0xf bank_mask:0xf bound_ctrl:1
	s_nop 1
	v_add_f32_dpp v64, v64, v64 quad_perm:[2,3,0,1] row_mask:0xf bank_mask:0xf bound_ctrl:1
	v_add_f32_dpp v65, v65, v65 quad_perm:[2,3,0,1] row_mask:0xf bank_mask:0xf bound_ctrl:1
	s_nop 1
	v_add_f32_dpp v64, v64, v64 row_half_mirror row_mask:0xf bank_mask:0xf bound_ctrl:1
	v_add_f32_dpp v65, v65, v65 row_half_mirror row_mask:0xf bank_mask:0xf bound_ctrl:1
	s_nop 1
	v_add_f32_dpp v64, v64, v64 row_mirror row_mask:0xf bank_mask:0xf bound_ctrl:1
	v_add_f32_dpp v65, v65, v65 row_mirror row_mask:0xf bank_mask:0xf bound_ctrl:1
	v_mul_f32_e32 v64, 0x3c800000, v64
	v_mul_f32_e32 v65, 0x3c800000, v65
	v_sub_f32_e32 v32, v32, v64
	v_sub_f32_e32 v36, v36, v65
	v_sub_f32_e32 v33, v33, v64
	v_sub_f32_e32 v37, v37, v65
	v_sub_f32_e32 v34, v34, v64
	v_sub_f32_e32 v38, v38, v65
	v_sub_f32_e32 v35, v35, v64
	v_sub_f32_e32 v39, v39, v65
	v_mul_f32_e32 v66, v32, v32
	v_fmac_f32_e32 v66, v33, v33
	v_mul_f32_e32 v3, v34, v34
	v_fmac_f32_e32 v3, v35, v35
	v_add_f32_e32 v66, v66, v3
	v_mul_f32_e32 v67, v36, v36
	v_fmac_f32_e32 v67, v37, v37
	v_mul_f32_e32 v3, v38, v38
	v_fmac_f32_e32 v3, v39, v39
	v_add_f32_e32 v67, v67, v3
	s_nop 1
	v_add_f32_dpp v66, v66, v66 quad_perm:[1,0,3,2] row_mask:0xf bank_mask:0xf bound_ctrl:1
	v_add_f32_dpp v67, v67, v67 quad_perm:[1,0,3,2] row_mask:0xf bank_mask:0xf bound_ctrl:1
	s_nop 1
	v_add_f32_dpp v66, v66, v66 quad_perm:[2,3,0,1] row_mask:0xf bank_mask:0xf bound_ctrl:1
	v_add_f32_dpp v67, v67, v67 quad_perm:[2,3,0,1] row_mask:0xf bank_mask:0xf bound_ctrl:1
	s_nop 1
	v_add_f32_dpp v66, v66, v66 row_half_mirror row_mask:0xf bank_mask:0xf bound_ctrl:1
	v_add_f32_dpp v67, v67, v67 row_half_mirror row_mask:0xf bank_mask:0xf bound_ctrl:1
	s_nop 1
	v_add_f32_dpp v66, v66, v66 row_mirror row_mask:0xf bank_mask:0xf bound_ctrl:1
	v_add_f32_dpp v67, v67, v67 row_mirror row_mask:0xf bank_mask:0xf bound_ctrl:1
	v_mov_b32_e32 v3, 0x3c800000
	v_mov_b32_e32 v5, 0x3a27c5ac
	v_fma_f32 v66, v66, v3, v5
	v_fma_f32 v67, v67, v3, v5
	v_rsq_f32_e32 v66, v66
	v_rsq_f32_e32 v67, v67
	s_nop 0
	v_mul_f32_e32 v32, v32, v66
	v_fma_f32 v32, v32, v112, v120
	v_add_f32_e32 v32, v32, v48
	v_mul_f32_e32 v32, v32, v56
	v_mul_f32_e32 v36, v36, v67
	v_fma_f32 v36, v36, v116, v124
	v_add_f32_e32 v36, v36, v52
	v_mul_f32_e32 v36, v36, v60
	v_mul_f32_e32 v33, v33, v66
	v_fma_f32 v33, v33, v113, v121
	v_add_f32_e32 v33, v33, v49
	v_mul_f32_e32 v33, v33, v57
	v_mul_f32_e32 v37, v37, v67
	v_fma_f32 v37, v37, v117, v125
	v_add_f32_e32 v37, v37, v53
	v_mul_f32_e32 v37, v37, v61
	v_mul_f32_e32 v34, v34, v66
	v_fma_f32 v34, v34, v114, v122
	v_add_f32_e32 v34, v34, v50
	v_mul_f32_e32 v34, v34, v58
	v_mul_f32_e32 v38, v38, v67
	v_fma_f32 v38, v38, v118, v126
	v_add_f32_e32 v38, v38, v54
	v_mul_f32_e32 v38, v38, v62
	v_mul_f32_e32 v35, v35, v66
	v_fma_f32 v35, v35, v115, v123
	v_add_f32_e32 v35, v35, v51
	v_mul_f32_e32 v35, v35, v59
	v_mul_f32_e32 v39, v39, v67
	v_fma_f32 v39, v39, v119, v127
	v_add_f32_e32 v39, v39, v55
	v_mul_f32_e32 v39, v39, v63
	v_mul_f32_e32 v3, v32, v32
	v_fmac_f32_e32 v3, v33, v33
	v_mul_f32_e32 v4, v34, v34
	v_fmac_f32_e32 v4, v35, v35
	v_add_f32_e32 v3, v3, v4
	v_mul_f32_e32 v5, v36, v36
	v_fmac_f32_e32 v5, v37, v37
	v_mul_f32_e32 v6, v38, v38
	v_fmac_f32_e32 v6, v39, v39
	v_add_f32_e32 v5, v5, v6
	v_add_f32_e32 v3, v3, v5
	s_nop 1
	v_add_f32_dpp v3, v3, v3 quad_perm:[1,0,3,2] row_mask:0xf bank_mask:0xf bound_ctrl:1
	s_nop 1
	v_add_f32_dpp v3, v3, v3 quad_perm:[2,3,0,1] row_mask:0xf bank_mask:0xf bound_ctrl:1
	s_nop 1
	v_add_f32_dpp v3, v3, v3 row_half_mirror row_mask:0xf bank_mask:0xf bound_ctrl:1
	s_nop 1
	v_add_f32_dpp v3, v3, v3 row_mirror row_mask:0xf bank_mask:0xf bound_ctrl:1
	s_nop 1
	v_readlane_b32 s0, v3, 0
	v_readlane_b32 s1, v3, 16
	v_readlane_b32 s8, v3, 32
	v_readlane_b32 s9, v3, 48
	s_nop 1
	v_mov_b32_e32 v4, s0
	v_add_f32_e32 v4, s1, v4
	v_add_f32_e32 v4, s8, v4
	v_add_f32_e32 v4, s9, v4
	v_mov_b32_e32 v5, 0x3b000000
	v_fma_f32 v4, v4, v5, v173
	v_rsq_f32_e32 v4, v4
	s_nop 0
	v_mul_f32_e32 v8, v32, v4
	v_mul_f32_e32 v8, v8, v96
	v_mul_f32_e32 v9, v33, v4
	v_mul_f32_e32 v9, v9, v97
	v_mul_f32_e32 v10, v34, v4
	v_mul_f32_e32 v10, v10, v98
	v_mul_f32_e32 v11, v35, v4
	v_mul_f32_e32 v11, v11, v99
	v_cvt_pk_bf16_f32 v12, v8, v9
	v_cvt_pk_bf16_f32 v13, v10, v11
	global_store_dwordx2 v2, v[12:13], s[26:27] offset:2048
	v_mul_f32_e32 v8, v36, v4
	v_mul_f32_e32 v8, v8, v100
	v_mul_f32_e32 v9, v37, v4
	v_mul_f32_e32 v9, v9, v101
	v_mul_f32_e32 v10, v38, v4
	v_mul_f32_e32 v10, v10, v102
	v_mul_f32_e32 v11, v39, v4
	v_mul_f32_e32 v11, v11, v103
	v_cvt_pk_bf16_f32 v12, v8, v9
	v_cvt_pk_bf16_f32 v13, v10, v11
	global_store_dwordx2 v2, v[12:13], s[26:27] offset:2560
	s_add_i32 s30, s30, s14
	s_cmpk_gt_i32 s30, 0x1fff
	s_cbranch_scc0 .Lgn_row
	s_branch .LBB0_65
; __device__ __forceinline__ unsigned cvt_pk_bf16(float lo, float hi) { unsigned r; asm volatile("v_cvt_pk_bf16_f32 %0, %1, %2" : "=v"(r) : "v"(lo), "v"(hi)); return r; }
; __device__ __forceinline__ float dot4(f32x4 a, f32x4 b) { return (a.x * b.x + a.y * b.y) + (a.z * b.z + a.w * b.w); }
; __device__ __forceinline__ void group_norm_rows(const float* Y, const float* RW, const LayerP& L, bf16* dst, int gw, int NGW, int lane) {
;     ...
;             if (gi == 2) {
;                 const int ca = 4 * lane, cb = 256 + 4 * lane;
;                 const float ma = row16_sum((a.x + a.y) + (a.z + a.w)) * (1.f / 64.f), mb = row16_sum((b.x + b.y) + (b.z + b.w)) * (1.f / 64.f);
;                 const f32x4 da = a - ma, db = b - mb;
;                 const float ra = rsqrtf(row16_sum(dot4(da, da)) * (1.f / 64.f) + 64e-5f), rb = rsqrtf(row16_sum(dot4(db, db)) * (1.f / 64.f) + 64e-5f);
;                 const f32x4 ga = *(const f32x4*)(L.rw_lng + ca), gb = *(const f32x4*)(L.rw_lng + cb), ba = *(const f32x4*)(L.rw_lnb + ca), bb = *(const f32x4*)(L.rw_lnb + cb);
;                 const f32x4 bna = *(const f32x4*)(RW + 7 * RWSZ + (size_t)m * GW + ca), bnb = *(const f32x4*)(RW + 7 * RWSZ + (size_t)m * GW + cb);
;                 const f32x4 gga = *(const f32x4*)(RW + 6 * RWSZ + (size_t)m * GW + ca), ggb = *(const f32x4*)(RW + 6 * RWSZ + (size_t)m * GW + cb);
;                 a = (da * ra * ga + ba + bna) * gga; b = (db * rb * gb + bb + bnb) * ggb;
;             }
;             const float ss = wave_sum(dot4(a, a) + dot4(b, b));
;             const float rstd = rsqrtf(ss * (1.f / GW) + 1e-6f);
;             const f32x4 na = ((const f32x4*)(L.out_norm + gi * GW))[lane], nb = ((const f32x4*)(L.out_norm + gi * GW))[64 + lane];
;             const f32x4 oa = a * rstd * na, ob = b * rstd * nb;
;             u32x2 w; w.x = pg8::cvt_pk_bf16(oa.x, oa.y); w.y = pg8::cvt_pk_bf16(oa.z, oa.w); ((u32x2*)(dst + (size_t)m * D + gi * GW))[lane] = w;
;             w.x = pg8::cvt_pk_bf16(ob.x, ob.y); w.y = pg8::cvt_pk_bf16(ob.z, ob.w); ((u32x2*)(dst + (size_t)m * D + gi * GW))[64 + lane] = w;
;         }
;     }
.Lgn2_row:
	s_lshl_b32 s0, s30, 13
	s_add_u32 s20, s18, s0
	s_addc_u32 s21, s19, 0
	s_add_u32 s20, s20, 0x1e200000
	s_addc_u32 s21, s21, 0
	s_lshl_b32 s0, s30, 11
	s_add_u32 s22, s18, s0
	s_addc_u32 s23, s19, 0
	s_add_u32 s24, s22, 0x1d200000
	s_addc_u32 s25, s23, 0
	s_add_u32 s22, s22, 0x1c200000
	s_addc_u32 s23, s23, 0
	s_lshl_b32 s0, s30, 12
	s_add_u32 s26, s18, s0
	s_addc_u32 s27, s19, 0
	s_add_u32 s26, s26, 0x22200000
	s_addc_u32 s27, s27, 0
	global_load_dwordx4 v[32:35], v1, s[20:21]
	global_load_dwordx4 v[36:39], v1, s[20:21] offset:1024
	global_load_dwordx4 v[48:51], v0, s[24:25]
	global_load_dwordx4 v[52:55], v0, s[24:25] offset:1024
	global_load_dwordx4 v[56:59], v0, s[22:23]
	global_load_dwordx4 v[60:63], v0, s[22:23] offset:1024
	s_waitcnt vmcnt(0)
	v_add_f32_e32 v64, v32, v33
	v_add_f32_e32 v3, v34, v35
	v_add_f32_e32 v64, v64, v3
	v_add_f32_e32 v65, v36, v37
	v_add_f32_e32 v3, v38, v39
	v_add_f32_e32 v65, v65, v3
	s_nop 1
	v_add_f32_dpp v64, v64, v64 quad_perm:[1,0,3,2] row_mask:0xf bank_mask:0xf bound_ctrl:1
	v_add_f32_dpp v65, v65, v65 quad_perm:[1,0,3,2] row_mask:0xf bank_mask:0xf bound_ctrl:1
	s_nop 1
	v_add_f32_dpp v64, v64, v64 quad_perm:[2,3,0,1] row_mask:0xf bank_mask:0xf bound_ctrl:1
	v_add_f32_dpp v65, v65, v65 quad_perm:[2,3,0,1] row_mask:0xf bank_mask:0xf bound_ctrl:1
	s_nop 1
	v_add_f32_dpp v64, v64, v64 row_half_mirror row_mask:0xf bank_mask:0xf bound_ctrl:1
	v_add_f32_dpp v65, v65, v65 row_half_mirror row_mask:0xf bank_mask:0xf bound_ctrl:1
	s_nop 1
	v_add_f32_dpp v64, v64, v64 row_mirror row_mask:0xf bank_mask:0xf bound_ctrl:1
	v_add_f32_dpp v65, v65, v65 row_mirror row_mask:0xf bank_mask:0xf bound_ctrl:1
	v_mul_f32_e32 v64, 0x3c800000, v64
	v_mul_f32_e32 v65, 0x3c800000, v65
	v_sub_f32_e32 v32, v32, v64
	v_sub_f32_e32 v36, v36, v65
	v_sub_f32_e32 v33, v33, v64
	v_sub_f32_e32 v37, v37, v65
	v_sub_f32_e32 v34, v34, v64
	v_sub_f32_e32 v38, v38, v65
	v_sub_f32_e32 v35, v35, v64
	v_sub_f32_e32 v39, v39, v65
	v_mul_f32_e32 v66, v32, v32
	v_fmac_f32_e32 v66, v33, v33
	v_mul_f32_e32 v3, v34, v34
	v_fmac_f32_e32 v3, v35, v35
	v_add_f32_e32 v66, v66, v3
	v_mul_f32_e32 v67, v36, v36
	v_fmac_f32_e32 v67, v37, v37
	v_mul_f32_e32 v3, v38, v38
	v_fmac_f32_e32 v3, v39, v39
	v_add_f32_e32 v67, v67, v3
	s_nop 1
	v_add_f32_dpp v66, v66, v66 quad_perm:[1,0,3,2] row_mask:0xf bank_mask:0xf bound_ctrl:1
	v_add_f32_dpp v67, v67, v67 quad_perm:[1,0,3,2] row_mask:0xf bank_mask:0xf bound_ctrl:1
	s_nop 1
	v_add_f32_dpp v66, v66, v66 quad_perm:[2,3,0,1] row_mask:0xf bank_mask:0xf bound_ctrl:1
	v_add_f32_dpp v67, v67, v67 quad_perm:[2,3,0,1] row_mask:0xf bank_mask:0xf bound_ctrl:1
	s_nop 1
	v_add_f32_dpp v66, v66, v66 row_half_mirror row_mask:0xf bank_mask:0xf bound_ctrl:1
	v_add_f32_dpp v67, v67, v67 row_half_mirror row_mask:0xf bank_mask:0xf bound_ctrl:1
	s_nop 1
	v_add_f32_dpp v66, v66, v66 row_mirror row_mask:0xf bank_mask:0xf bound_ctrl:1
	v_add_f32_dpp v67, v67, v67 row_mirror row_mask:0xf bank_mask:0xf bound_ctrl:1
	v_mov_b32_e32 v3, 0x3c800000
	v_mov_b32_e32 v5, 0x3a27c5ac
	v_fma_f32 v66, v66, v3, v5
	v_fma_f32 v67, v67, v3, v5
	v_rsq_f32_e32 v66, v66
	v_rsq_f32_e32 v67, v67
	s_nop 0
	v_mul_f32_e32 v32, v32, v66
	v_fma_f32 v32, v32, v112, v120
	v_add_f32_e32 v32, v32, v48
	v_mul_f32_e32 v32, v32, v56
	v_mul_f32_e32 v36, v36, v67
	v_fma_f32 v36, v36, v116, v124
	v_add_f32_e32 v36, v36, v52
	v_mul_f32_e32 v36, v36, v60
	v_mul_f32_e32 v33, v33, v66
	v_fma_f32 v33, v33, v113, v121
	v_add_f32_e32 v33, v33, v49
	v_mul_f32_e32 v33, v33, v57
	v_mul_f32_e32 v37, v37, v67
	v_fma_f32 v37, v37, v117, v125
	v_add_f32_e32 v37, v37, v53
	v_mul_f32_e32 v37, v37, v61
	v_mul_f32_e32 v34, v34, v66
	v_fma_f32 v34, v34, v114, v122
	v_add_f32_e32 v34, v34, v50
	v_mul_f32_e32 v34, v34, v58
	v_mul_f32_e32 v38, v38, v67
	v_fma_f32 v38, v38, v118, v126
	v_add_f32_e32 v38, v38, v54
	v_mul_f32_e32 v38, v38, v62
	v_mul_f32_e32 v35, v35, v66
	v_fma_f32 v35, v35, v115, v123
	v_add_f32_e32 v35, v35, v51
	v_mul_f32_e32 v35, v35, v59
	v_mul_f32_e32 v39, v39, v67
	v_fma_f32 v39, v39, v119, v127
	v_add_f32_e32 v39, v39, v55
	v_mul_f32_e32 v39, v39, v63
	v_mul_f32_e32 v3, v32, v32
	v_fmac_f32_e32 v3, v33, v33
	v_mul_f32_e32 v4, v34, v34
	v_fmac_f32_e32 v4, v35, v35
	v_add_f32_e32 v3, v3, v4
	v_mul_f32_e32 v5, v36, v36
	v_fmac_f32_e32 v5, v37, v37
	v_mul_f32_e32 v6, v38, v38
	v_fmac_f32_e32 v6, v39, v39
	v_add_f32_e32 v5, v5, v6
	v_add_f32_e32 v3, v3, v5
	s_nop 1
	v_add_f32_dpp v3, v3, v3 quad_perm:[1,0,3,2] row_mask:0xf bank_mask:0xf bound_ctrl:1
	s_nop 1
	v_add_f32_dpp v3, v3, v3 quad_perm:[2,3,0,1] row_mask:0xf bank_mask:0xf bound_ctrl:1
	s_nop 1
	v_add_f32_dpp v3, v3, v3 row_half_mirror row_mask:0xf bank_mask:0xf bound_ctrl:1
	s_nop 1
	v_add_f32_dpp v3, v3, v3 row_mirror row_mask:0xf bank_mask:0xf bound_ctrl:1
	s_nop 1
	v_readlane_b32 s0, v3, 0
	v_readlane_b32 s1, v3, 16
	v_readlane_b32 s8, v3, 32
	v_readlane_b32 s9, v3, 48
	s_nop 1
	v_mov_b32_e32 v4, s0
	v_add_f32_e32 v4, s1, v4
	v_add_f32_e32 v4, s8, v4
	v_add_f32_e32 v4, s9, v4
	v_mov_b32_e32 v5, 0x3b000000
	v_fma_f32 v4, v4, v5, v173
	v_rsq_f32_e32 v4, v4
	s_nop 0
	v_mul_f32_e32 v8, v32, v4
	v_mul_f32_e32 v8, v8, v96
	v_mul_f32_e32 v9, v33, v4
	v_mul_f32_e32 v9, v9, v97
	v_mul_f32_e32 v10, v34, v4
	v_mul_f32_e32 v10, v10, v98
	v_mul_f32_e32 v11, v35, v4
	v_mul_f32_e32 v11, v11, v99
	v_cvt_pk_bf16_f32 v12, v8, v9
	v_cvt_pk_bf16_f32 v13, v10, v11
	global_store_dwordx2 v2, v[12:13], s[26:27] offset:2048
	v_mul_f32_e32 v8, v36, v4
	v_mul_f32_e32 v8, v8, v100
	v_mul_f32_e32 v9, v37, v4
	v_mul_f32_e32 v9, v9, v101
	v_mul_f32_e32 v10, v38, v4
	v_mul_f32_e32 v10, v10, v102
	v_mul_f32_e32 v11, v39, v4
	v_mul_f32_e32 v11, v11, v103
	v_cvt_pk_bf16_f32 v12, v8, v9
	v_cvt_pk_bf16_f32 v13, v10, v11
	global_store_dwordx2 v2, v[12:13], s[26:27] offset:2560
	s_add_i32 s30, s30, s14
	s_cmpk_gt_i32 s30, 0x1fff
	s_cbranch_scc0 .Lgn2_row

; __device__ __forceinline__ float dot4(f32x4 a, f32x4 b) { return (a.x * b.x + a.y * b.y) + (a.z * b.z + a.w * b.w); }
; __device__ __forceinline__ void group_norm_rows(const float* Y, const float* RW, const LayerP& L, bf16* dst, int gw, int NGW, int lane) {
;     for (int m = gw; m < T; m += NGW) {
; #pragma unroll
;         for (int gi = 0; gi < 4; ++gi) {
;             const float* yr = Y + (size_t)m * D + gi * GW;
;             f32x4 a = ((const f32x4*)yr)[lane], b = ((const f32x4*)yr)[64 + lane];
;             if (gi == 2) {
;                 const int ca = 4 * lane, cb = 256 + 4 * lane;
;                 const float ma = row16_sum((a.x + a.y) + (a.z + a.w)) * (1.f / 64.f), mb = row16_sum((b.x + b.y) + (b.z + b.w)) * (1.f / 64.f);
;                 const f32x4 da = a - ma, db = b - mb;
;                 const float ra = rsqrtf(row16_sum(dot4(da, da)) * (1.f / 64.f) + 64e-5f), rb = rsqrtf(row16_sum(dot4(db, db)) * (1.f / 64.f) + 64e-5f);
;                 const f32x4 ga = *(const f32x4*)(L.rw_lng + ca), gb = *(const f32x4*)(L.rw_lng + cb), ba = *(const f32x4*)(L.rw_lnb + ca), bb = *(const f32x4*)(L.rw_lnb + cb);
;                 const f32x4 bna = *(const f32x4*)(RW + 7 * RWSZ + (size_t)m * GW + ca), bnb = *(const f32x4*)(RW + 7 * RWSZ + (size_t)m * GW + cb);
;                 const f32x4 gga = *(const f32x4*)(RW + 6 * RWSZ + (size_t)m * GW + ca), ggb = *(const f32x4*)(RW + 6 * RWSZ + (size_t)m * GW + cb);
;                 a = (da * ra * ga + ba + bna) * gga; b = (db * rb * gb + bb + bnb) * ggb;
;             }
;             const float ss = wave_sum(dot4(a, a) + dot4(b, b));
;             const float rstd = rsqrtf(ss * (1.f / GW) + 1e-6f);
;             const f32x4 na = ((const f32x4*)(L.out_norm + gi * GW))[lane], nb = ((const f32x4*)(L.out_norm + gi * GW))[64 + lane];
; __global__ void __launch_bounds__(NTHR, 2) hymba_fwd(Args args) {
;     ...
;         } else if (k == 8) {
;     ...
;             for (int tb = 0; tb < NCH * 8; tb += 4 * G) rw_scan4(tid, ldsf, WSP(float, WS_RW), tb + (tid >> 7) * G + bid, NCH * 8, 2, WSP(float, WS_SIN), nullptr, WSP(float, WS_Y));
.LBB0_66:
	v_readlane_b32 s0, v254, 29
	s_cmp_gt_i32 s0, 7
	s_mov_b64 s[0:1], -1
	s_cbranch_scc0 .LBB0_91
	v_readlane_b32 s0, v254, 38
	s_cmp_lg_u32 s0, 0x100
	s_cbranch_scc1 .Lp8_main
	v_readlane_b32 s0, v254, 44
	s_cmp_lt_u32 s0, 4
	s_cbranch_scc1 .Lp8_main
	v_readlane_b32 s1, v254, 39
	s_sub_i32 s0, s0, 4
	s_lshl_b32 s1, s1, 2
	s_add_i32 s30, s1, s0
	s_mov_b32 s28, 0
	s_waitcnt vmcnt(0) lgkmcnt(0)
	v_readlane_b32 s8, v254, 32
	v_readlane_b32 s9, v254, 33
	v_readlane_b32 s10, v254, 30
	s_nop 0
	s_load_dwordx2 s[4:5], s[8:9], 0x140
	s_load_dwordx4 s[20:23], s[8:9], 0xf8
	s_ashr_i32 s11, s10, 31
	v_lshlrev_b32_e32 v0, 4, v188
	v_add_u32_e32 v1, 0x1000, v0
	v_lshlrev_b32_e32 v2, 3, v188
	s_lshl_b64 s[0:1], s[10:11], 13
	s_lshl_b64 s[6:7], s[10:11], 11
	s_waitcnt lgkmcnt(0)
	s_add_u32 s4, s4, s0
	s_addc_u32 s5, s5, s1
	s_add_u32 s20, s20, s6
	s_addc_u32 s21, s21, s7
	s_add_u32 s22, s22, s6
	s_addc_u32 s23, s23, s7
	global_load_dwordx4 v[80:83], v0, s[4:5] offset:0
	global_load_dwordx4 v[84:87], v0, s[4:5] offset:1024
	global_load_dwordx4 v[88:91], v0, s[4:5] offset:2048
	global_load_dwordx4 v[92:95], v0, s[4:5] offset:3072
	global_load_dwordx4 v[96:99], v1, s[4:5] offset:0
	global_load_dwordx4 v[100:103], v1, s[4:5] offset:1024
	global_load_dwordx4 v[104:107], v1, s[4:5] offset:2048
	global_load_dwordx4 v[108:111], v1, s[4:5] offset:3072
	global_load_dwordx4 v[112:115], v0, s[20:21]
	global_load_dwordx4 v[116:119], v0, s[20:21] offset:1024
	global_load_dwordx4 v[120:123], v0, s[22:23]
	global_load_dwordx4 v[124:127], v0, s[22:23] offset:1024
; __device__ __forceinline__ unsigned cvt_pk_bf16(float lo, float hi) { unsigned r; asm volatile("v_cvt_pk_bf16_f32 %0, %1, %2" : "=v"(r) : "v"(lo), "v"(hi)); return r; }
; __device__ __forceinline__ float dot4(f32x4 a, f32x4 b) { return (a.x * b.x + a.y * b.y) + (a.z * b.z + a.w * b.w); }
; __device__ __forceinline__ void group_norm_rows(const float* Y, const float* RW, const LayerP& L, bf16* dst, int gw, int NGW, int lane) {
;     for (int m = gw; m < T; m += NGW) {
; #pragma unroll
;         for (int gi = 0; gi < 4; ++gi) {
;             const float* yr = Y + (size_t)m * D + gi * GW;
;             f32x4 a = ((const f32x4*)yr)[lane], b = ((const f32x4*)yr)[64 + lane];
;             if (gi == 2) {
;                 const int ca = 4 * lane, cb = 256 + 4 * lane;
;                 const float ma = row16_sum((a.x + a.y) + (a.z + a.w)) * (1.f / 64.f), mb = row16_sum((b.x + b.y) + (b.z + b.w)) * (1.f / 64.f);
;                 const f32x4 da = a - ma, db = b - mb;
;                 const float ra = rsqrtf(row16_sum(dot4(da, da)) * (1.f / 64.f) + 64e-5f), rb = rsqrtf(row16_sum(dot4(db, db)) * (1.f / 64.f) + 64e-5f);
;                 const f32x4 ga = *(const f32x4*)(L.rw_lng + ca), gb = *(const f32x4*)(L.rw_lng + cb), ba = *(const f32x4*)(L.rw_lnb + ca), bb = *(const f32x4*)(L.rw_lnb + cb);
;                 const f32x4 bna = *(const f32x4*)(RW + 7 * RWSZ + (size_t)m * GW + ca), bnb = *(const f32x4*)(RW + 7 * RWSZ + (size_t)m * GW + cb);
;                 const f32x4 gga = *(const f32x4*)(RW + 6 * RWSZ + (size_t)m * GW + ca), ggb = *(const f32x4*)(RW + 6 * RWSZ + (size_t)m * GW + cb);
;                 a = (da * ra * ga + ba + bna) * gga; b = (db * rb * gb + bb + bnb) * ggb;
;             }
;             const float ss = wave_sum(dot4(a, a) + dot4(b, b));
;             const float rstd = rsqrtf(ss * (1.f / GW) + 1e-6f);
;             const f32x4 na = ((const f32x4*)(L.out_norm + gi * GW))[lane], nb = ((const f32x4*)(L.out_norm + gi * GW))[64 + lane];
;             const f32x4 oa = a * rstd * na, ob = b * rstd * nb;
;             u32x2 w; w.x = pg8::cvt_pk_bf16(oa.x, oa.y); w.y = pg8::cvt_pk_bf16(oa.z, oa.w); ((u32x2*)(dst + (size_t)m * D + gi * GW))[lane] = w;
;             w.x = pg8::cvt_pk_bf16(ob.x, ob.y); w.y = pg8::cvt_pk_bf16(ob.z, ob.w); ((u32x2*)(dst + (size_t)m * D + gi * GW))[64 + lane] = w;
;         }
;     }
.Lgs_row:
	s_lshl_b32 s0, s30, 13
	s_add_u32 s20, s18, s0
	s_addc_u32 s21, s19, 0
	s_add_u32 s20, s20, 0x1e200000
	s_addc_u32 s21, s21, 0
	s_lshl_b32 s0, s30, 11
	s_add_u32 s22, s18, s0
	s_addc_u32 s23, s19, 0
	s_add_u32 s24, s22, 0x1d200000
	s_addc_u32 s25, s23, 0
	s_add_u32 s22, s22, 0x1c200000
	s_addc_u32 s23, s23, 0
	s_lshl_b32 s0, s30, 12
	s_add_u32 s26, s18, s0
	s_addc_u32 s27, s19, 0
	s_add_u32 s26, s26, 0x22200000
	s_addc_u32 s27, s27, 0
	global_load_dwordx4 v[16:19], v0, s[20:21]
	global_load_dwordx4 v[20:23], v0, s[20:21] offset:1024
	global_load_dwordx4 v[24:27], v0, s[20:21] offset:2048
	global_load_dwordx4 v[28:31], v0, s[20:21] offset:3072
	global_load_dwordx4 v[40:43], v1, s[20:21] offset:2048
	global_load_dwordx4 v[44:47], v1, s[20:21] offset:3072
	s_waitcnt vmcnt(4)
	v_mul_f32_e32 v3, v16, v16
	v_fmac_f32_e32 v3, v17, v17
	v_mul_f32_e32 v4, v18, v18
	v_fmac_f32_e32 v4, v19, v19
	v_add_f32_e32 v3, v3, v4
	v_mul_f32_e32 v5, v20, v20
	v_fmac_f32_e32 v5, v21, v21
	v_mul_f32_e32 v6, v22, v22
	v_fmac_f32_e32 v6, v23, v23
	v_add_f32_e32 v5, v5, v6
	v_add_f32_e32 v3, v3, v5
	s_nop 1
	v_add_f32_dpp v3, v3, v3 quad_perm:[1,0,3,2] row_mask:0xf bank_mask:0xf bound_ctrl:1
	s_nop 1
	v_add_f32_dpp v3, v3, v3 quad_perm:[2,3,0,1] row_mask:0xf bank_mask:0xf bound_ctrl:1
	s_nop 1
	v_add_f32_dpp v3, v3, v3 row_half_mirror row_mask:0xf bank_mask:0xf bound_ctrl:1
	s_nop 1
	v_add_f32_dpp v3, v3, v3 row_mirror row_mask:0xf bank_mask:0xf bound_ctrl:1
	s_nop 1
	v_readlane_b32 s0, v3, 0
	v_readlane_b32 s1, v3, 16
	v_readlane_b32 s8, v3, 32
	v_readlane_b32 s9, v3, 48
	s_nop 1
	v_mov_b32_e32 v4, s0
	v_add_f32_e32 v4, s1, v4
	v_add_f32_e32 v4, s8, v4
	v_add_f32_e32 v4, s9, v4
	v_mov_b32_e32 v5, 0x3b000000
	v_fma_f32 v4, v4, v5, v173
	v_rsq_f32_e32 v4, v4
	s_nop 0
	v_mul_f32_e32 v8, v16, v4
	v_mul_f32_e32 v8, v8, v80
	v_mul_f32_e32 v9, v17, v4
	v_mul_f32_e32 v9, v9, v81
	v_mul_f32_e32 v10, v18, v4
	v_mul_f32_e32 v10, v10, v82
	v_mul_f32_e32 v11, v19, v4
	v_mul_f32_e32 v11, v11, v83
	v_cvt_pk_bf16_f32 v12, v8, v9
	v_cvt_pk_bf16_f32 v13, v10, v11
	global_store_dwordx2 v2, v[12:13], s[26:27] offset:0
	v_mul_f32_e32 v8, v20, v4
	v_mul_f32_e32 v8, v8, v84
	v_mul_f32_e32 v9, v21, v4
	v_mul_f32_e32 v9, v9, v85
	v_mul_f32_e32 v10, v22, v4
	v_mul_f32_e32 v10, v10, v86
	v_mul_f32_e32 v11, v23, v4
	v_mul_f32_e32 v11, v11, v87
	v_cvt_pk_bf16_f32 v12, v8, v9
	v_cvt_pk_bf16_f32 v13, v10, v11
	global_store_dwordx2 v2, v[12:13], s[26:27] offset:512
	s_waitcnt vmcnt(4)
	v_mul_f32_e32 v3, v24, v24
	v_fmac_f32_e32 v3, v25, v25
	v_mul_f32_e32 v4, v26, v26
	v_fmac_f32_e32 v4, v27, v27
	v_add_f32_e32 v3, v3, v4
	v_mul_f32_e32 v5, v28, v28
	v_fmac_f32_e32 v5, v29, v29
	v_mul_f32_e32 v6, v30, v30
	v_fmac_f32_e32 v6, v31, v31
	v_add_f32_e32 v5, v5, v6
	v_add_f32_e32 v3, v3, v5
	s_nop 1
	v_add_f32_dpp v3, v3, v3 quad_perm:[1,0,3,2] row_mask:0xf bank_mask:0xf bound_ctrl:1
	s_nop 1
	v_add_f32_dpp v3, v3, v3 quad_perm:[2,3,0,1] row_mask:0xf bank_mask:0xf bound_ctrl:1
	s_nop 1
	v_add_f32_dpp v3, v3, v3 row_half_mirror row_mask:0xf bank_mask:0xf bound_ctrl:1
	s_nop 1
	v_add_f32_dpp v3, v3, v3 row_mirror row_mask:0xf bank_mask:0xf bound_ctrl:1
	s_nop 1
	v_readlane_b32 s0, v3, 0
	v_readlane_b32 s1, v3, 16
	v_readlane_b32 s8, v3, 32
	v_readlane_b32 s9, v3, 48
	s_nop 1
	v_mov_b32_e32 v4, s0
	v_add_f32_e32 v4, s1, v4
	v_add_f32_e32 v4, s8, v4
	v_add_f32_e32 v4, s9, v4
	v_mov_b32_e32 v5, 0x3b000000
	v_fma_f32 v4, v4, v5, v173
	v_rsq_f32_e32 v4, v4
	s_nop 0
	v_mul_f32_e32 v8, v24, v4
	v_mul_f32_e32 v8, v8, v88
	v_mul_f32_e32 v9, v25, v4
	v_mul_f32_e32 v9, v9, v89
	v_mul_f32_e32 v10, v26, v4
	v_mul_f32_e32 v10, v10, v90
	v_mul_f32_e32 v11, v27, v4
	v_mul_f32_e32 v11, v11, v91
	v_cvt_pk_bf16_f32 v12, v8, v9
	v_cvt_pk_bf16_f32 v13, v10, v11
	global_store_dwordx2 v2, v[12:13], s[26:27] offset:1024
	v_mul_f32_e32 v8, v28, v4
	v_mul_f32_e32 v8, v8, v92
	v_mul_f32_e32 v9, v29, v4
	v_mul_f32_e32 v9, v9, v93
	v_mul_f32_e32 v10, v30, v4
	v_mul_f32_e32 v10, v10, v94
	v_mul_f32_e32 v11, v31, v4
	v_mul_f32_e32 v11, v11, v95
	v_cvt_pk_bf16_f32 v12, v8, v9
	v_cvt_pk_bf16_f32 v13, v10, v11
	global_store_dwordx2 v2, v[12:13], s[26:27] offset:1536
	s_waitcnt vmcnt(4)
	v_mul_f32_e32 v3, v40, v40
	v_fmac_f32_e32 v3, v41, v41
	v_mul_f32_e32 v4, v42, v42
	v_fmac_f32_e32 v4, v43, v43
	v_add_f32_e32 v3, v3, v4
	v_mul_f32_e32 v5, v44, v44
	v_fmac_f32_e32 v5, v45, v45
	v_mul_f32_e32 v6, v46, v46
	v_fmac_f32_e32 v6, v47, v47
	v_add_f32_e32 v5, v5, v6
	v_add_f32_e32 v3, v3, v5
	s_nop 1
	v_add_f32_dpp v3, v3, v3 quad_perm:[1,0,3,2] row_mask:0xf bank_mask:0xf bound_ctrl:1
	s_nop 1
	v_add_f32_dpp v3, v3, v3 quad_perm:[2,3,0,1] row_mask:0xf bank_mask:0xf bound_ctrl:1
	s_nop 1
	v_add_f32_dpp v3, v3, v3 row_half_mirror row_mask:0xf bank_mask:0xf bound_ctrl:1
	s_nop 1
	v_add_f32_dpp v3, v3, v3 row_mirror row_mask:0xf bank_mask:0xf bound_ctrl:1
	s_nop 1
	v_readlane_b32 s0, v3, 0
	v_readlane_b32 s1, v3, 16
	v_readlane_b32 s8, v3, 32
	v_readlane_b32 s9, v3, 48
	s_nop 1
	v_mov_b32_e32 v4, s0
	v_add_f32_e32 v4, s1, v4
	v_add_f32_e32 v4, s8, v4
	v_add_f32_e32 v4, s9, v4
	v_mov_b32_e32 v5, 0x3b000000
	v_fma_f32 v4, v4, v5, v173
	v_rsq_f32_e32 v4, v4
	s_nop 0
	v_mul_f32_e32 v8, v40, v4
	v_mul_f32_e32 v8, v8, v104
	v_mul_f32_e32 v9, v41, v4
	v_mul_f32_e32 v9, v9, v105
	v_mul_f32_e32 v10, v42, v4
	v_mul_f32_e32 v10, v10, v106
	v_mul_f32_e32 v11, v43, v4
	v_mul_f32_e32 v11, v11, v107
	v_cvt_pk_bf16_f32 v12, v8, v9
	v_cvt_pk_bf16_f32 v13, v10, v11
	global_store_dwordx2 v2, v[12:13], s[26:27] offset:3072
	v_mul_f32_e32 v8, v44, v4
	v_mul_f32_e32 v8, v8, v108
	v_mul_f32_e32 v9, v45, v4
	v_mul_f32_e32 v9, v9, v109
	v_mul_f32_e32 v10, v46, v4
	v_mul_f32_e32 v10, v10, v110
	v_mul_f32_e32 v11, v47, v4
	v_mul_f32_e32 v11, v11, v111
	v_cvt_pk_bf16_f32 v12, v8, v9
	v_cvt_pk_bf16_f32 v13, v10, v11
	global_store_dwordx2 v2, v[12:13], s[26:27] offset:3584
	s_cmp_ge_u32 s28, 18
	s_cbranch_scc1 .Lgs_nobar
	s_barrier
	s_add_i32 s28, s28, 1
.Lgs_nobar:
	s_addk_i32 s30, 0x400
	s_cmpk_gt_i32 s30, 0x1fff
	s_cbranch_scc0 .Lgs_row
.Lgs_drain:
	s_cmp_ge_u32 s28, 18
	s_cbranch_scc1 .Lgs_done
	s_barrier
	s_add_i32 s28, s28, 1
	s_branch .Lgs_drain

; #define LAS __attribute__((address_space(3)))
; __device__ __forceinline__ void rw_scan4(const int tid, LAS float* lds, const float* RW, int task, int ntasks, int mode, const float* SIN, float* PQ, float* Y) {
;     const int slot = tid >> 7, sl = tid & 127, kp = sl & 7, rg = sl >> 3;
;     const bool active = task < ntasks;
;     int head = 0, c = 0, kind = 2;
;     if (active) { if (mode == 0) { kind = task & 1; head = (task >> 1) & 7; c = task >> 4; } else { head = task & 7; c = task >> 3; } }
;     const int t0 = c * CHL;
;     f32x2 s[4][4];
;     if (kind == 2 && active) {
;         const float* ip = SIN + (size_t)(head * NCH + c) * 4096 + (rg * 4) * 64 + kp * 8;
; #pragma unroll
;         for (int j = 0; j < 4; ++j) { const f32x4 i0 = *(const f32x4*)(ip + j * 64), i1 = *(const f32x4*)(ip + j * 64 + 4);
;             s[j][0] = (f32x2){i0.x, i0.y}; s[j][1] = (f32x2){i0.z, i0.w}; s[j][2] = (f32x2){i1.x, i1.y}; s[j][3] = (f32x2){i1.z, i1.w}; }
;     } else {
; #pragma unroll
;         for (int j = 0; j < 4; ++j)
; #pragma unroll
;             for (int i = 0; i < 4; ++i) { const int kk = kp * 8 + 2 * i, rr = rg * 4 + j; s[j][i] = (f32x2){(kind == 1 && kk == rr) ? 1.f : 0.f, (kind == 1 && kk + 1 == rr) ? 1.f : 0.f}; }
;     }
;     LAS float* sb = lds + slot * (2 * 6 * TB * 64);
;     const int srow = sl >> 4, sc4 = sl & 15;
;     const float* gsrc = RW + (size_t)(t0 + srow) * GW + head * 64 + sc4 * 4;
;     f32x4 st[6];
;     constexpr int nb = CHL / TB;
;     __syncthreads();
;     if (active) {
; #pragma unroll
;         for (int a = 0; a < 6; ++a) st[a] = *(const f32x4*)(gsrc + a * RWSZ);
; #pragma unroll
;         for (int a = 0; a < 6; ++a) *(LAS f32x4*)(sb + (a * TB + srow) * 64 + sc4 * 4) = st[a];
;     }
;     __syncthreads();
.Lp8_main:
	s_waitcnt vmcnt(5)
	v_ashrrev_i32_e32 v0, 7, v148
	v_mul_lo_u32 v1, v0, s45
	s_waitcnt vmcnt(4)
	v_bfe_u32 v6, v148, 3, 4
	s_movk_i32 s4, 0x6000
	v_add_u32_e32 v76, s44, v1
	v_and_b32_e32 v1, 7, v148
	v_mul_lo_u32 v7, v0, s4
	v_lshlrev_b32_e32 v0, 2, v148
	v_lshlrev_b32_e32 v4, 10, v6
	v_mov_b32_e32 v5, v144
	v_bfe_u32 v77, v148, 4, 3
	v_and_b32_e32 v0, 60, v0
	v_lshlrev_b32_e32 v2, 5, v1
	s_waitcnt lgkmcnt(0)
	v_lshl_add_u64 v[4:5], s[18:19], 0, v[4:5]
	v_mov_b32_e32 v3, v144
	s_waitcnt vmcnt(3)
	v_add_u32_e32 v8, 0, v7
	v_lshlrev_b32_e32 v9, 2, v0
	v_cmp_eq_u32_e64 s[38:39], 0, v1
	v_lshl_add_u64 v[4:5], v[4:5], 0, v[2:3]
	s_mov_b64 s[4:5], 0x29300000
	v_lshlrev_b32_e32 v1, 8, v77
	v_lshl_add_u64 v[56:57], v[4:5], 0, s[4:5]
	v_add3_u32 v78, v8, v9, v1
	v_lshl_or_b32 v1, v6, 4, v7
	v_readlane_b32 s4, v254, 15
	s_add_u32 s0, s18, 0x16200000
	s_addc_u32 s1, s19, 0
	v_add_u32_e32 v79, s4, v1
	v_or_b32_e32 v1, v7, v2
	v_add_u32_e32 v80, 0, v1
	v_lshlrev_b32_e32 v1, 1, v148
	v_and_b32_e32 v2, 0xf0, v1
	s_mov_b32 s14, 0
	s_lshl_b32 s15, s45, 2
	v_lshl_add_u64 v[58:59], s[18:19], 0, v[2:3]
	v_lshlrev_b32_e32 v60, 2, v0
	v_mov_b32_e32 v81, v76
	s_branch .LBB0_69
